# main fast-epilogue stores write-through (sc0 sc1) instead of nt: output lines leave L2, less dirty data to flush at the grid barrier
# speedup vs baseline: 1.0236x; 1.0059x over previous
.LBB0_372:
	s_add_u32 s8, s6, 0xfff80080
	s_addc_u32 s9, s7, -1
	s_add_i32 s21, 0, 0x10000
	v_add_u32_e32 v143, s21, v167
	ds_read_b128 v[148:151], v143
	ds_read_b128 v[152:155], v143 offset:1024
	ds_read_b128 v[156:159], v143 offset:2048
	ds_read_b128 v[160:163], v143 offset:3072
	s_cmp_eq_u32 s20, 28
	s_cselect_b32 s11, s17, s9
	s_cselect_b32 s10, s16, s8
	s_cselect_b32 s9, s19, s15
	s_cselect_b32 s8, s18, s13
	v_lshl_add_u64 v[164:165], s[6:7], 0, v[138:139]
	s_add_i32 m0, s40, 0xc000
	ds_read_b128 v[172:175], v171
	ds_read_b128 v[180:183], v171 offset:1024
	ds_read_b128 v[184:187], v171 offset:2048
	ds_read_b128 v[188:191], v171 offset:3072
	ds_read_b128 v[192:195], v171 offset:4096
	ds_read_b128 v[196:199], v171 offset:5120
	ds_read_b128 v[200:203], v171 offset:6144
	ds_read_b128 v[204:207], v171 offset:7168
	global_load_lds_dwordx4 v[164:165], off
	v_lshl_add_u64 v[164:165], s[6:7], 0, v[140:141]
	s_add_i32 m0, s40, 0xe000
	s_nop 0
	global_load_lds_dwordx4 v[164:165], off
	s_waitcnt lgkmcnt(8)
	s_barrier
	s_waitcnt lgkmcnt(0)
	s_setprio 1
	s_waitcnt lgkmcnt(0)
	v_mfma_f32_16x16x32_bf16 v[126:129], v[148:151], v[172:175], v[126:129]
	v_mfma_f32_16x16x32_bf16 v[122:125], v[156:159], v[172:175], v[122:125]
	v_mfma_f32_16x16x32_bf16 v[110:113], v[148:151], v[184:187], v[110:113]
	v_mfma_f32_16x16x32_bf16 v[106:109], v[156:159], v[184:187], v[106:109]
	v_mfma_f32_16x16x32_bf16 v[94:97], v[148:151], v[192:195], v[94:97]
	v_mfma_f32_16x16x32_bf16 v[90:93], v[156:159], v[192:195], v[90:93]
	v_mfma_f32_16x16x32_bf16 v[78:81], v[148:151], v[200:203], v[78:81]
	v_mfma_f32_16x16x32_bf16 v[74:77], v[156:159], v[200:203], v[74:77]
	v_mfma_f32_16x16x32_bf16 v[126:129], v[152:155], v[180:183], v[126:129]
	v_mfma_f32_16x16x32_bf16 v[122:125], v[160:163], v[180:183], v[122:125]
	v_mfma_f32_16x16x32_bf16 v[110:113], v[152:155], v[188:191], v[110:113]
	v_mfma_f32_16x16x32_bf16 v[106:109], v[160:163], v[188:191], v[106:109]
	v_mfma_f32_16x16x32_bf16 v[94:97], v[152:155], v[196:199], v[94:97]
	v_mfma_f32_16x16x32_bf16 v[90:93], v[160:163], v[196:199], v[90:93]
	v_mfma_f32_16x16x32_bf16 v[78:81], v[152:155], v[204:207], v[78:81]
	v_mfma_f32_16x16x32_bf16 v[74:77], v[160:163], v[204:207], v[74:77]
	s_setprio 0
	s_barrier
	s_add_i32 s24, 0, 0x14000
	s_add_i32 s21, s21, s39
	v_add_u32_e32 v143, s24, v167
	v_lshl_add_u64 v[164:165], s[8:9], 0, v[134:135]
	s_mov_b32 m0, s21
	ds_read_b128 v[208:211], v143
	ds_read_b128 v[212:215], v143 offset:1024
	ds_read_b128 v[216:219], v143 offset:2048
	ds_read_b128 v[220:223], v143 offset:3072
	global_load_lds_dwordx4 v[164:165], off
	v_lshl_add_u64 v[176:177], s[8:9], 0, v[130:131]
	s_add_i32 m0, s21, 0x2000
	s_nop 0
	global_load_lds_dwordx4 v[176:177], off
	s_barrier
	s_waitcnt lgkmcnt(0)
	s_setprio 1
	s_waitcnt lgkmcnt(0)
	v_mfma_f32_16x16x32_bf16 v[118:121], v[208:211], v[172:175], v[118:121]
	v_mfma_f32_16x16x32_bf16 v[114:117], v[216:219], v[172:175], v[114:117]
	v_mfma_f32_16x16x32_bf16 v[102:105], v[208:211], v[184:187], v[102:105]
	v_mfma_f32_16x16x32_bf16 v[98:101], v[216:219], v[184:187], v[98:101]
	v_mfma_f32_16x16x32_bf16 v[86:89], v[208:211], v[192:195], v[86:89]
	v_mfma_f32_16x16x32_bf16 v[82:85], v[216:219], v[192:195], v[82:85]
	v_mfma_f32_16x16x32_bf16 v[70:73], v[208:211], v[200:203], v[70:73]
	v_mfma_f32_16x16x32_bf16 v[66:69], v[216:219], v[200:203], v[66:69]
	v_mfma_f32_16x16x32_bf16 v[118:121], v[212:215], v[180:183], v[118:121]
	v_mfma_f32_16x16x32_bf16 v[114:117], v[220:223], v[180:183], v[114:117]
	v_mfma_f32_16x16x32_bf16 v[102:105], v[212:215], v[188:191], v[102:105]
	v_mfma_f32_16x16x32_bf16 v[98:101], v[220:223], v[188:191], v[98:101]
	v_mfma_f32_16x16x32_bf16 v[86:89], v[212:215], v[196:199], v[86:89]
	v_mfma_f32_16x16x32_bf16 v[82:85], v[220:223], v[196:199], v[82:85]
	v_mfma_f32_16x16x32_bf16 v[70:73], v[212:215], v[204:207], v[70:73]
	v_mfma_f32_16x16x32_bf16 v[66:69], v[220:223], v[204:207], v[66:69]
	s_setprio 0
	s_mov_b32 m0, s40
	v_lshl_add_u64 v[224:225], s[10:11], 0, v[136:137]
	s_barrier
	ds_read_b128 v[172:175], v171 offset:16384
	ds_read_b128 v[180:183], v171 offset:17408
	ds_read_b128 v[184:187], v171 offset:18432
	ds_read_b128 v[188:191], v171 offset:19456
	ds_read_b128 v[192:195], v171 offset:20480
	ds_read_b128 v[196:199], v171 offset:21504
	ds_read_b128 v[200:203], v171 offset:22528
	ds_read_b128 v[204:207], v171 offset:23552
	global_load_lds_dwordx4 v[224:225], off
	v_lshl_add_u64 v[236:237], s[10:11], 0, v[132:133]
	s_mov_b32 m0, s41
	s_nop 0
	global_load_lds_dwordx4 v[236:237], off
	s_barrier
	s_waitcnt lgkmcnt(0)
	s_setprio 1
	s_waitcnt lgkmcnt(0)
	v_mfma_f32_16x16x32_bf16 v[62:65], v[148:151], v[172:175], v[62:65]
	v_mfma_f32_16x16x32_bf16 v[58:61], v[156:159], v[172:175], v[58:61]
	v_mfma_f32_16x16x32_bf16 v[46:49], v[148:151], v[184:187], v[46:49]
	v_mfma_f32_16x16x32_bf16 v[42:45], v[156:159], v[184:187], v[42:45]
	v_mfma_f32_16x16x32_bf16 v[28:31], v[148:151], v[192:195], v[28:31]
	v_mfma_f32_16x16x32_bf16 v[24:27], v[156:159], v[192:195], v[24:27]
	v_mfma_f32_16x16x32_bf16 v[12:15], v[148:151], v[200:203], v[12:15]
	v_mfma_f32_16x16x32_bf16 v[8:11], v[156:159], v[200:203], v[8:11]
	v_mfma_f32_16x16x32_bf16 v[62:65], v[152:155], v[180:183], v[62:65]
	v_mfma_f32_16x16x32_bf16 v[58:61], v[160:163], v[180:183], v[58:61]
	v_mfma_f32_16x16x32_bf16 v[46:49], v[152:155], v[188:191], v[46:49]
	v_mfma_f32_16x16x32_bf16 v[42:45], v[160:163], v[188:191], v[42:45]
	v_mfma_f32_16x16x32_bf16 v[28:31], v[152:155], v[196:199], v[28:31]
	v_mfma_f32_16x16x32_bf16 v[24:27], v[160:163], v[196:199], v[24:27]
	v_mfma_f32_16x16x32_bf16 v[12:15], v[152:155], v[204:207], v[12:15]
	v_mfma_f32_16x16x32_bf16 v[8:11], v[160:163], v[204:207], v[8:11]
	s_setprio 0
	s_barrier
	s_add_u32 s22, s8, 0x80000
	s_addc_u32 s23, s9, 0
	s_add_i32 s21, s24, s39
	v_lshl_add_u64 v[148:149], s[22:23], 0, v[134:135]
	s_mov_b32 m0, s21
	s_nop 0
	global_load_lds_dwordx4 v[148:149], off
	v_lshl_add_u64 v[148:149], s[22:23], 0, v[130:131]
	s_add_i32 m0, s21, 0x2000
	s_nop 0
	global_load_lds_dwordx4 v[148:149], off
	s_waitcnt vmcnt(6)
	s_barrier
	s_setprio 1
	v_mfma_f32_16x16x32_bf16 v[54:57], v[208:211], v[172:175], v[54:57]
	v_mfma_f32_16x16x32_bf16 v[50:53], v[216:219], v[172:175], v[50:53]
	v_mfma_f32_16x16x32_bf16 v[38:41], v[208:211], v[184:187], v[38:41]
	v_mfma_f32_16x16x32_bf16 v[34:37], v[216:219], v[184:187], v[34:37]
	v_mfma_f32_16x16x32_bf16 v[20:23], v[208:211], v[192:195], v[20:23]
	v_mfma_f32_16x16x32_bf16 v[16:19], v[216:219], v[192:195], v[16:19]
	v_mfma_f32_16x16x32_bf16 v[4:7], v[208:211], v[200:203], v[4:7]
	v_mfma_f32_16x16x32_bf16 v[0:3], v[216:219], v[200:203], v[0:3]
	v_mfma_f32_16x16x32_bf16 v[54:57], v[212:215], v[180:183], v[54:57]
	v_mfma_f32_16x16x32_bf16 v[50:53], v[220:223], v[180:183], v[50:53]
	v_mfma_f32_16x16x32_bf16 v[38:41], v[212:215], v[188:191], v[38:41]
	v_mfma_f32_16x16x32_bf16 v[34:37], v[220:223], v[188:191], v[34:37]
	v_mfma_f32_16x16x32_bf16 v[20:23], v[212:215], v[196:199], v[20:23]
	v_mfma_f32_16x16x32_bf16 v[16:19], v[220:223], v[196:199], v[16:19]
	v_mfma_f32_16x16x32_bf16 v[4:7], v[212:215], v[204:207], v[4:7]
	v_mfma_f32_16x16x32_bf16 v[0:3], v[220:223], v[204:207], v[0:3]
	s_setprio 0
	s_add_i32 s21, 0, 0x18000
	v_add_u32_e32 v143, s21, v167
	s_barrier
	ds_read_b128 v[148:151], v143
	ds_read_b128 v[152:155], v143 offset:1024
	ds_read_b128 v[156:159], v143 offset:2048
	ds_read_b128 v[160:163], v143 offset:3072
	s_add_u32 s10, s10, 0x80000
	s_addc_u32 s11, s11, 0
	s_mov_b32 m0, s42
	v_lshl_add_u64 v[208:209], s[10:11], 0, v[136:137]
	ds_read_b128 v[172:175], v171 offset:32768
	ds_read_b128 v[180:183], v171 offset:33792
	ds_read_b128 v[184:187], v171 offset:34816
	ds_read_b128 v[188:191], v171 offset:35840
	ds_read_b128 v[192:195], v171 offset:36864
	ds_read_b128 v[196:199], v171 offset:37888
	ds_read_b128 v[200:203], v171 offset:38912
	ds_read_b128 v[204:207], v171 offset:39936
	global_load_lds_dwordx4 v[208:209], off
	v_lshl_add_u64 v[208:209], s[10:11], 0, v[132:133]
	s_mov_b32 m0, s43
	s_nop 0
	global_load_lds_dwordx4 v[208:209], off
	s_waitcnt lgkmcnt(8)
	s_barrier
	s_waitcnt lgkmcnt(0)
	s_setprio 1
	s_waitcnt lgkmcnt(0)
	v_mfma_f32_16x16x32_bf16 v[126:129], v[148:151], v[172:175], v[126:129]
	v_mfma_f32_16x16x32_bf16 v[122:125], v[156:159], v[172:175], v[122:125]
	v_mfma_f32_16x16x32_bf16 v[110:113], v[148:151], v[184:187], v[110:113]
	v_mfma_f32_16x16x32_bf16 v[106:109], v[156:159], v[184:187], v[106:109]
	v_mfma_f32_16x16x32_bf16 v[94:97], v[148:151], v[192:195], v[94:97]
	v_mfma_f32_16x16x32_bf16 v[90:93], v[156:159], v[192:195], v[90:93]
	v_mfma_f32_16x16x32_bf16 v[78:81], v[148:151], v[200:203], v[78:81]
	v_mfma_f32_16x16x32_bf16 v[74:77], v[156:159], v[200:203], v[74:77]
	v_mfma_f32_16x16x32_bf16 v[126:129], v[152:155], v[180:183], v[126:129]
	v_mfma_f32_16x16x32_bf16 v[122:125], v[160:163], v[180:183], v[122:125]
	v_mfma_f32_16x16x32_bf16 v[110:113], v[152:155], v[188:191], v[110:113]
	v_mfma_f32_16x16x32_bf16 v[106:109], v[160:163], v[188:191], v[106:109]
	v_mfma_f32_16x16x32_bf16 v[94:97], v[152:155], v[196:199], v[94:97]
	v_mfma_f32_16x16x32_bf16 v[90:93], v[160:163], v[196:199], v[90:93]
	v_mfma_f32_16x16x32_bf16 v[78:81], v[152:155], v[204:207], v[78:81]
	v_mfma_f32_16x16x32_bf16 v[74:77], v[160:163], v[204:207], v[74:77]
	s_setprio 0
	s_barrier
	s_add_i32 s10, 0, 0x1c000
	s_add_i32 s11, s21, s39
	v_add_u32_e32 v143, s10, v167
	v_lshl_add_u64 v[164:165], v[164:165], 0, s[88:89]
	s_mov_b32 m0, s11
	ds_read_b128 v[208:211], v143
	ds_read_b128 v[212:215], v143 offset:1024
	ds_read_b128 v[216:219], v143 offset:2048
	ds_read_b128 v[220:223], v143 offset:3072
	global_load_lds_dwordx4 v[164:165], off
	v_lshl_add_u64 v[164:165], v[176:177], 0, s[88:89]
	s_add_i32 m0, s11, 0x2000
	s_nop 0
	global_load_lds_dwordx4 v[164:165], off
	s_barrier
	s_waitcnt lgkmcnt(0)
	s_setprio 1
	s_waitcnt lgkmcnt(0)
	v_mfma_f32_16x16x32_bf16 v[118:121], v[208:211], v[172:175], v[118:121]
	v_mfma_f32_16x16x32_bf16 v[114:117], v[216:219], v[172:175], v[114:117]
	v_mfma_f32_16x16x32_bf16 v[102:105], v[208:211], v[184:187], v[102:105]
	v_mfma_f32_16x16x32_bf16 v[98:101], v[216:219], v[184:187], v[98:101]
	v_mfma_f32_16x16x32_bf16 v[86:89], v[208:211], v[192:195], v[86:89]
	v_mfma_f32_16x16x32_bf16 v[82:85], v[216:219], v[192:195], v[82:85]
	v_mfma_f32_16x16x32_bf16 v[70:73], v[208:211], v[200:203], v[70:73]
	v_mfma_f32_16x16x32_bf16 v[66:69], v[216:219], v[200:203], v[66:69]
	v_mfma_f32_16x16x32_bf16 v[118:121], v[212:215], v[180:183], v[118:121]
	v_mfma_f32_16x16x32_bf16 v[114:117], v[220:223], v[180:183], v[114:117]
	v_mfma_f32_16x16x32_bf16 v[102:105], v[212:215], v[188:191], v[102:105]
	v_mfma_f32_16x16x32_bf16 v[98:101], v[220:223], v[188:191], v[98:101]
	v_mfma_f32_16x16x32_bf16 v[86:89], v[212:215], v[196:199], v[86:89]
	v_mfma_f32_16x16x32_bf16 v[82:85], v[220:223], v[196:199], v[82:85]
	v_mfma_f32_16x16x32_bf16 v[70:73], v[212:215], v[204:207], v[70:73]
	v_mfma_f32_16x16x32_bf16 v[66:69], v[220:223], v[204:207], v[66:69]
	s_setprio 0
	s_mov_b32 m0, s46
	v_lshl_add_u64 v[164:165], v[224:225], 0, s[88:89]
	s_barrier
	ds_read_b128 v[172:175], v171 offset:49152
	ds_read_b128 v[180:183], v171 offset:50176
	ds_read_b128 v[184:187], v171 offset:51200
	ds_read_b128 v[188:191], v171 offset:52224
	ds_read_b128 v[192:195], v171 offset:53248
	ds_read_b128 v[196:199], v171 offset:54272
	ds_read_b128 v[200:203], v171 offset:55296
	ds_read_b128 v[204:207], v171 offset:56320
	global_load_lds_dwordx4 v[164:165], off
	v_lshl_add_u64 v[164:165], v[236:237], 0, s[88:89]
	s_mov_b32 m0, s47
	s_nop 0
	global_load_lds_dwordx4 v[164:165], off
	s_barrier
	s_waitcnt lgkmcnt(0)
	s_setprio 1
	s_waitcnt lgkmcnt(0)
	v_mfma_f32_16x16x32_bf16 v[62:65], v[148:151], v[172:175], v[62:65]
	v_mfma_f32_16x16x32_bf16 v[58:61], v[156:159], v[172:175], v[58:61]
	v_mfma_f32_16x16x32_bf16 v[46:49], v[148:151], v[184:187], v[46:49]
	v_mfma_f32_16x16x32_bf16 v[42:45], v[156:159], v[184:187], v[42:45]
	v_mfma_f32_16x16x32_bf16 v[28:31], v[148:151], v[192:195], v[28:31]
	v_mfma_f32_16x16x32_bf16 v[24:27], v[156:159], v[192:195], v[24:27]
	v_mfma_f32_16x16x32_bf16 v[12:15], v[148:151], v[200:203], v[12:15]
	v_mfma_f32_16x16x32_bf16 v[8:11], v[156:159], v[200:203], v[8:11]
	v_mfma_f32_16x16x32_bf16 v[62:65], v[152:155], v[180:183], v[62:65]
	v_mfma_f32_16x16x32_bf16 v[58:61], v[160:163], v[180:183], v[58:61]
	v_mfma_f32_16x16x32_bf16 v[46:49], v[152:155], v[188:191], v[46:49]
	v_mfma_f32_16x16x32_bf16 v[42:45], v[160:163], v[188:191], v[42:45]
	v_mfma_f32_16x16x32_bf16 v[28:31], v[152:155], v[196:199], v[28:31]
	v_mfma_f32_16x16x32_bf16 v[24:27], v[160:163], v[196:199], v[24:27]
	v_mfma_f32_16x16x32_bf16 v[12:15], v[152:155], v[204:207], v[12:15]
	v_mfma_f32_16x16x32_bf16 v[8:11], v[160:163], v[204:207], v[8:11]
	s_setprio 0
	s_barrier
	s_add_u32 s8, s8, 0x80080
	s_addc_u32 s9, s9, 0
	s_add_i32 s10, s10, s39
	v_lshl_add_u64 v[148:149], s[8:9], 0, v[134:135]
	s_mov_b32 m0, s10
	s_nop 0
	global_load_lds_dwordx4 v[148:149], off
	v_lshl_add_u64 v[148:149], s[8:9], 0, v[130:131]
	s_add_i32 m0, s10, 0x2000
	s_nop 0
	global_load_lds_dwordx4 v[148:149], off
	s_waitcnt vmcnt(6)
	s_barrier
	s_setprio 1
	v_mfma_f32_16x16x32_bf16 v[54:57], v[208:211], v[172:175], v[54:57]
	v_mfma_f32_16x16x32_bf16 v[50:53], v[216:219], v[172:175], v[50:53]
	v_mfma_f32_16x16x32_bf16 v[38:41], v[208:211], v[184:187], v[38:41]
	v_mfma_f32_16x16x32_bf16 v[34:37], v[216:219], v[184:187], v[34:37]
	v_mfma_f32_16x16x32_bf16 v[20:23], v[208:211], v[192:195], v[20:23]
	v_mfma_f32_16x16x32_bf16 v[16:19], v[216:219], v[192:195], v[16:19]
	v_mfma_f32_16x16x32_bf16 v[4:7], v[208:211], v[200:203], v[4:7]
	v_mfma_f32_16x16x32_bf16 v[0:3], v[216:219], v[200:203], v[0:3]
	v_mfma_f32_16x16x32_bf16 v[54:57], v[212:215], v[180:183], v[54:57]
	v_mfma_f32_16x16x32_bf16 v[50:53], v[220:223], v[180:183], v[50:53]
	v_mfma_f32_16x16x32_bf16 v[38:41], v[212:215], v[188:191], v[38:41]
	v_mfma_f32_16x16x32_bf16 v[34:37], v[220:223], v[188:191], v[34:37]
	v_mfma_f32_16x16x32_bf16 v[20:23], v[212:215], v[196:199], v[20:23]
	v_mfma_f32_16x16x32_bf16 v[16:19], v[220:223], v[196:199], v[16:19]
	v_mfma_f32_16x16x32_bf16 v[4:7], v[212:215], v[204:207], v[4:7]
	v_mfma_f32_16x16x32_bf16 v[0:3], v[220:223], v[204:207], v[0:3]
	s_setprio 0
	s_add_i32 s20, s20, 2
	s_add_u32 s6, s6, 0x100
	s_addc_u32 s7, s7, 0
	s_add_u32 s13, s13, 0x100
	s_addc_u32 s15, s15, 0
	s_cmp_gt_u32 s20, 29
	s_barrier
	s_cbranch_scc0 .LBB0_372
	s_sub_i32 s6, s51, 8
	s_cmp_lt_u32 s6, 8
	s_cbranch_scc1 .Lmain_old
	s_sub_i32 s6, s51, 32
	s_cmp_lt_u32 s6, 12
	s_cbranch_scc1 .Lmain_kv
	v_mbcnt_lo_u32_b32 v217, -1, 0
	v_mbcnt_hi_u32_b32 v217, -1, v217
	v_lshrrev_b32_e32 v208, 4, v217
	v_bfe_u32 v209, v217, 2, 2
	v_and_b32_e32 v210, 3, v217
	v_lshl_add_u32 v216, v208, 2, v209
	v_lshl_add_u32 v217, v210, 4, v216
	v_lshlrev_b32_e32 v217, 2, v217
	v_add_u32_e32 v216, s45, v216
	v_lshlrev_b32_e32 v210, 4, v210
	s_lshl_b32 s6, s44, 6
	v_add_u32_e32 v210, s6, v210
	s_cmp_ge_u32 s51, 0x44
	s_cbranch_scc1 .Lmain_sig
	s_sub_i32 s6, s51, 44
	s_mov_b32 s7, 0x25e51000
	s_mov_b32 s13, 0x15e51000
	s_cmp_lt_i32 s6, 0
	s_cselect_b32 s6, s51, s6
	s_cselect_b32 s7, s13, s7
	s_lshr_b32 s13, s6, 3
	s_lshl_b32 s13, s13, 26
	s_add_i32 s7, s7, s13
	s_and_b32 s6, s6, 7
	s_lshl_b32 s6, s6, 9
	s_add_i32 s7, s7, s6
	s_lshl_b32 s6, s31, 20
	s_add_i32 s7, s7, s6
	s_add_u32 s22, s76, s7
	s_addc_u32 s23, s77, 0
	v_lshl_add_u32 v216, v216, 12, v210
	s_lshr_b32 s6, s51, 3
	s_cmp_eq_u32 s6, 3
	s_cbranch_scc1 .Lmain_q
	s_add_u32 s10, s22, 0
	s_addc_u32 s11, s23, 0
	v_cvt_pk_bf16_f32 v148, v126, v127
	v_cvt_pk_bf16_f32 v149, v128, v129
	v_cvt_pk_bf16_f32 v150, v122, v123
	v_cvt_pk_bf16_f32 v151, v124, v125
	ds_bpermute_b32 v180, v217, v148
	ds_bpermute_b32 v181, v217, v149
	ds_bpermute_b32 v182, v217, v150
	ds_bpermute_b32 v183, v217, v151
	v_cvt_pk_bf16_f32 v152, v118, v119
	v_cvt_pk_bf16_f32 v153, v120, v121
	v_cvt_pk_bf16_f32 v154, v114, v115
	v_cvt_pk_bf16_f32 v155, v116, v117
	ds_bpermute_b32 v184, v217, v152
	ds_bpermute_b32 v185, v217, v153
	ds_bpermute_b32 v186, v217, v154
	ds_bpermute_b32 v187, v217, v155
	s_add_u32 s20, s22, 0x10000
	s_addc_u32 s21, s23, 0
	v_cvt_pk_bf16_f32 v156, v110, v111
	v_cvt_pk_bf16_f32 v157, v112, v113
	v_cvt_pk_bf16_f32 v158, v106, v107
	v_cvt_pk_bf16_f32 v159, v108, v109
	ds_bpermute_b32 v188, v217, v156
	ds_bpermute_b32 v189, v217, v157
	ds_bpermute_b32 v190, v217, v158
	ds_bpermute_b32 v191, v217, v159
	v_cvt_pk_bf16_f32 v160, v102, v103
	v_cvt_pk_bf16_f32 v161, v104, v105
	v_cvt_pk_bf16_f32 v162, v98, v99
	v_cvt_pk_bf16_f32 v163, v100, v101
	ds_bpermute_b32 v192, v217, v160
	ds_bpermute_b32 v193, v217, v161
	ds_bpermute_b32 v194, v217, v162
	ds_bpermute_b32 v195, v217, v163
	s_waitcnt lgkmcnt(0)
	global_store_dwordx4 v216, v[180:183], s[10:11] sc0 sc1
	global_store_dwordx4 v216, v[184:187], s[10:11] offset:256 sc0 sc1
	global_store_dwordx4 v216, v[188:191], s[20:21] sc0 sc1
	global_store_dwordx4 v216, v[192:195], s[20:21] offset:256 sc0 sc1
	s_add_u32 s10, s22, 0x20000
	s_addc_u32 s11, s23, 0
	v_cvt_pk_bf16_f32 v148, v94, v95
	v_cvt_pk_bf16_f32 v149, v96, v97
	v_cvt_pk_bf16_f32 v150, v90, v91
	v_cvt_pk_bf16_f32 v151, v92, v93
	ds_bpermute_b32 v180, v217, v148
	ds_bpermute_b32 v181, v217, v149
	ds_bpermute_b32 v182, v217, v150
	ds_bpermute_b32 v183, v217, v151
	v_cvt_pk_bf16_f32 v152, v86, v87
	v_cvt_pk_bf16_f32 v153, v88, v89
	v_cvt_pk_bf16_f32 v154, v82, v83
	v_cvt_pk_bf16_f32 v155, v84, v85
	ds_bpermute_b32 v184, v217, v152
	ds_bpermute_b32 v185, v217, v153
	ds_bpermute_b32 v186, v217, v154
	ds_bpermute_b32 v187, v217, v155
	s_add_u32 s20, s22, 0x30000
	s_addc_u32 s21, s23, 0
	v_cvt_pk_bf16_f32 v156, v78, v79
	v_cvt_pk_bf16_f32 v157, v80, v81
	v_cvt_pk_bf16_f32 v158, v74, v75
	v_cvt_pk_bf16_f32 v159, v76, v77
	ds_bpermute_b32 v188, v217, v156
	ds_bpermute_b32 v189, v217, v157
	ds_bpermute_b32 v190, v217, v158
	ds_bpermute_b32 v191, v217, v159
	v_cvt_pk_bf16_f32 v160, v70, v71
	v_cvt_pk_bf16_f32 v161, v72, v73
	v_cvt_pk_bf16_f32 v162, v66, v67
	v_cvt_pk_bf16_f32 v163, v68, v69
	ds_bpermute_b32 v192, v217, v160
	ds_bpermute_b32 v193, v217, v161
	ds_bpermute_b32 v194, v217, v162
	ds_bpermute_b32 v195, v217, v163
	s_waitcnt lgkmcnt(0)
	global_store_dwordx4 v216, v[180:183], s[10:11] sc0 sc1
	global_store_dwordx4 v216, v[184:187], s[10:11] offset:256 sc0 sc1
	global_store_dwordx4 v216, v[188:191], s[20:21] sc0 sc1
	global_store_dwordx4 v216, v[192:195], s[20:21] offset:256 sc0 sc1
	s_add_u32 s10, s22, 0x80000
	s_addc_u32 s11, s23, 0
	v_cvt_pk_bf16_f32 v148, v62, v63
	v_cvt_pk_bf16_f32 v149, v64, v65
	v_cvt_pk_bf16_f32 v150, v58, v59
	v_cvt_pk_bf16_f32 v151, v60, v61
	ds_bpermute_b32 v180, v217, v148
	ds_bpermute_b32 v181, v217, v149
	ds_bpermute_b32 v182, v217, v150
	ds_bpermute_b32 v183, v217, v151
	v_cvt_pk_bf16_f32 v152, v54, v55
	v_cvt_pk_bf16_f32 v153, v56, v57
	v_cvt_pk_bf16_f32 v154, v50, v51
	v_cvt_pk_bf16_f32 v155, v52, v53
	ds_bpermute_b32 v184, v217, v152
	ds_bpermute_b32 v185, v217, v153
	ds_bpermute_b32 v186, v217, v154
	ds_bpermute_b32 v187, v217, v155
	s_add_u32 s20, s22, 0x90000
	s_addc_u32 s21, s23, 0
	v_cvt_pk_bf16_f32 v156, v46, v47
	v_cvt_pk_bf16_f32 v157, v48, v49
	v_cvt_pk_bf16_f32 v158, v42, v43
	v_cvt_pk_bf16_f32 v159, v44, v45
	ds_bpermute_b32 v188, v217, v156
	ds_bpermute_b32 v189, v217, v157
	ds_bpermute_b32 v190, v217, v158
	ds_bpermute_b32 v191, v217, v159
	v_cvt_pk_bf16_f32 v160, v38, v39
	v_cvt_pk_bf16_f32 v161, v40, v41
	v_cvt_pk_bf16_f32 v162, v34, v35
	v_cvt_pk_bf16_f32 v163, v36, v37
	ds_bpermute_b32 v192, v217, v160
	ds_bpermute_b32 v193, v217, v161
	ds_bpermute_b32 v194, v217, v162
	ds_bpermute_b32 v195, v217, v163
	s_waitcnt lgkmcnt(0)
	global_store_dwordx4 v216, v[180:183], s[10:11] sc0 sc1
	global_store_dwordx4 v216, v[184:187], s[10:11] offset:256 sc0 sc1
	global_store_dwordx4 v216, v[188:191], s[20:21] sc0 sc1
	global_store_dwordx4 v216, v[192:195], s[20:21] offset:256 sc0 sc1
	s_add_u32 s10, s22, 0xa0000
	s_addc_u32 s11, s23, 0
	v_cvt_pk_bf16_f32 v148, v28, v29
	v_cvt_pk_bf16_f32 v149, v30, v31
	v_cvt_pk_bf16_f32 v150, v24, v25
	v_cvt_pk_bf16_f32 v151, v26, v27
	ds_bpermute_b32 v180, v217, v148
	ds_bpermute_b32 v181, v217, v149
	ds_bpermute_b32 v182, v217, v150
	ds_bpermute_b32 v183, v217, v151
	v_cvt_pk_bf16_f32 v152, v20, v21
	v_cvt_pk_bf16_f32 v153, v22, v23
	v_cvt_pk_bf16_f32 v154, v16, v17
	v_cvt_pk_bf16_f32 v155, v18, v19
	ds_bpermute_b32 v184, v217, v152
	ds_bpermute_b32 v185, v217, v153
	ds_bpermute_b32 v186, v217, v154
	ds_bpermute_b32 v187, v217, v155
	s_add_u32 s20, s22, 0xb0000
	s_addc_u32 s21, s23, 0
	v_cvt_pk_bf16_f32 v156, v12, v13
	v_cvt_pk_bf16_f32 v157, v14, v15
	v_cvt_pk_bf16_f32 v158, v8, v9
	v_cvt_pk_bf16_f32 v159, v10, v11
	ds_bpermute_b32 v188, v217, v156
	ds_bpermute_b32 v189, v217, v157
	ds_bpermute_b32 v190, v217, v158
	ds_bpermute_b32 v191, v217, v159
	v_cvt_pk_bf16_f32 v160, v4, v5
	v_cvt_pk_bf16_f32 v161, v6, v7
	v_cvt_pk_bf16_f32 v162, v0, v1
	v_cvt_pk_bf16_f32 v163, v2, v3
	ds_bpermute_b32 v192, v217, v160
	ds_bpermute_b32 v193, v217, v161
	ds_bpermute_b32 v194, v217, v162
	ds_bpermute_b32 v195, v217, v163
	s_waitcnt lgkmcnt(0)
	global_store_dwordx4 v216, v[180:183], s[10:11] sc0 sc1
	global_store_dwordx4 v216, v[184:187], s[10:11] offset:256 sc0 sc1
	global_store_dwordx4 v216, v[188:191], s[20:21] sc0 sc1
	global_store_dwordx4 v216, v[192:195], s[20:21] offset:256 sc0 sc1
	s_branch .LBB0_364
.Lmain_q:
	s_mov_b32 s6, 0x3e0293ee
	s_add_u32 s10, s22, 0
	s_addc_u32 s11, s23, 0
	v_pk_mul_f32 v[126:127], v[126:127], s[6:7] op_sel_hi:[1,0]
	v_pk_mul_f32 v[128:129], v[128:129], s[6:7] op_sel_hi:[1,0]
	v_pk_mul_f32 v[122:123], v[122:123], s[6:7] op_sel_hi:[1,0]
	v_pk_mul_f32 v[124:125], v[124:125], s[6:7] op_sel_hi:[1,0]
	v_cvt_pk_bf16_f32 v148, v126, v127
	v_cvt_pk_bf16_f32 v149, v128, v129
	v_cvt_pk_bf16_f32 v150, v122, v123
	v_cvt_pk_bf16_f32 v151, v124, v125
	ds_bpermute_b32 v180, v217, v148
	ds_bpermute_b32 v181, v217, v149
	ds_bpermute_b32 v182, v217, v150
	ds_bpermute_b32 v183, v217, v151
	v_pk_mul_f32 v[118:119], v[118:119], s[6:7] op_sel_hi:[1,0]
	v_pk_mul_f32 v[120:121], v[120:121], s[6:7] op_sel_hi:[1,0]
	v_pk_mul_f32 v[114:115], v[114:115], s[6:7] op_sel_hi:[1,0]
	v_pk_mul_f32 v[116:117], v[116:117], s[6:7] op_sel_hi:[1,0]
	v_cvt_pk_bf16_f32 v152, v118, v119
	v_cvt_pk_bf16_f32 v153, v120, v121
	v_cvt_pk_bf16_f32 v154, v114, v115
	v_cvt_pk_bf16_f32 v155, v116, v117
	ds_bpermute_b32 v184, v217, v152
	ds_bpermute_b32 v185, v217, v153
	ds_bpermute_b32 v186, v217, v154
	ds_bpermute_b32 v187, v217, v155
	s_add_u32 s20, s22, 0x10000
	s_addc_u32 s21, s23, 0
	v_pk_mul_f32 v[110:111], v[110:111], s[6:7] op_sel_hi:[1,0]
	v_pk_mul_f32 v[112:113], v[112:113], s[6:7] op_sel_hi:[1,0]
	v_pk_mul_f32 v[106:107], v[106:107], s[6:7] op_sel_hi:[1,0]
	v_pk_mul_f32 v[108:109], v[108:109], s[6:7] op_sel_hi:[1,0]
	v_cvt_pk_bf16_f32 v156, v110, v111
	v_cvt_pk_bf16_f32 v157, v112, v113
	v_cvt_pk_bf16_f32 v158, v106, v107
	v_cvt_pk_bf16_f32 v159, v108, v109
	ds_bpermute_b32 v188, v217, v156
	ds_bpermute_b32 v189, v217, v157
	ds_bpermute_b32 v190, v217, v158
	ds_bpermute_b32 v191, v217, v159
	v_pk_mul_f32 v[102:103], v[102:103], s[6:7] op_sel_hi:[1,0]
	v_pk_mul_f32 v[104:105], v[104:105], s[6:7] op_sel_hi:[1,0]
	v_pk_mul_f32 v[98:99], v[98:99], s[6:7] op_sel_hi:[1,0]
	v_pk_mul_f32 v[100:101], v[100:101], s[6:7] op_sel_hi:[1,0]
	v_cvt_pk_bf16_f32 v160, v102, v103
	v_cvt_pk_bf16_f32 v161, v104, v105
	v_cvt_pk_bf16_f32 v162, v98, v99
	v_cvt_pk_bf16_f32 v163, v100, v101
	ds_bpermute_b32 v192, v217, v160
	ds_bpermute_b32 v193, v217, v161
	ds_bpermute_b32 v194, v217, v162
	ds_bpermute_b32 v195, v217, v163
	s_waitcnt lgkmcnt(0)
	global_store_dwordx4 v216, v[180:183], s[10:11] sc0 sc1
	global_store_dwordx4 v216, v[184:187], s[10:11] offset:256 sc0 sc1
	global_store_dwordx4 v216, v[188:191], s[20:21] sc0 sc1
	global_store_dwordx4 v216, v[192:195], s[20:21] offset:256 sc0 sc1
	s_add_u32 s10, s22, 0x20000
	s_addc_u32 s11, s23, 0
	v_pk_mul_f32 v[94:95], v[94:95], s[6:7] op_sel_hi:[1,0]
	v_pk_mul_f32 v[96:97], v[96:97], s[6:7] op_sel_hi:[1,0]
	v_pk_mul_f32 v[90:91], v[90:91], s[6:7] op_sel_hi:[1,0]
	v_pk_mul_f32 v[92:93], v[92:93], s[6:7] op_sel_hi:[1,0]
	v_cvt_pk_bf16_f32 v148, v94, v95
	v_cvt_pk_bf16_f32 v149, v96, v97
	v_cvt_pk_bf16_f32 v150, v90, v91
	v_cvt_pk_bf16_f32 v151, v92, v93
	ds_bpermute_b32 v180, v217, v148
	ds_bpermute_b32 v181, v217, v149
	ds_bpermute_b32 v182, v217, v150
	ds_bpermute_b32 v183, v217, v151
	v_pk_mul_f32 v[86:87], v[86:87], s[6:7] op_sel_hi:[1,0]
	v_pk_mul_f32 v[88:89], v[88:89], s[6:7] op_sel_hi:[1,0]
	v_pk_mul_f32 v[82:83], v[82:83], s[6:7] op_sel_hi:[1,0]
	v_pk_mul_f32 v[84:85], v[84:85], s[6:7] op_sel_hi:[1,0]
	v_cvt_pk_bf16_f32 v152, v86, v87
	v_cvt_pk_bf16_f32 v153, v88, v89
	v_cvt_pk_bf16_f32 v154, v82, v83
	v_cvt_pk_bf16_f32 v155, v84, v85
	ds_bpermute_b32 v184, v217, v152
	ds_bpermute_b32 v185, v217, v153
	ds_bpermute_b32 v186, v217, v154
	ds_bpermute_b32 v187, v217, v155
	s_add_u32 s20, s22, 0x30000
	s_addc_u32 s21, s23, 0
	v_pk_mul_f32 v[78:79], v[78:79], s[6:7] op_sel_hi:[1,0]
	v_pk_mul_f32 v[80:81], v[80:81], s[6:7] op_sel_hi:[1,0]
	v_pk_mul_f32 v[74:75], v[74:75], s[6:7] op_sel_hi:[1,0]
	v_pk_mul_f32 v[76:77], v[76:77], s[6:7] op_sel_hi:[1,0]
	v_cvt_pk_bf16_f32 v156, v78, v79
	v_cvt_pk_bf16_f32 v157, v80, v81
	v_cvt_pk_bf16_f32 v158, v74, v75
	v_cvt_pk_bf16_f32 v159, v76, v77
	ds_bpermute_b32 v188, v217, v156
	ds_bpermute_b32 v189, v217, v157
	ds_bpermute_b32 v190, v217, v158
	ds_bpermute_b32 v191, v217, v159
	v_pk_mul_f32 v[70:71], v[70:71], s[6:7] op_sel_hi:[1,0]
	v_pk_mul_f32 v[72:73], v[72:73], s[6:7] op_sel_hi:[1,0]
	v_pk_mul_f32 v[66:67], v[66:67], s[6:7] op_sel_hi:[1,0]
	v_pk_mul_f32 v[68:69], v[68:69], s[6:7] op_sel_hi:[1,0]
	v_cvt_pk_bf16_f32 v160, v70, v71
	v_cvt_pk_bf16_f32 v161, v72, v73
	v_cvt_pk_bf16_f32 v162, v66, v67
	v_cvt_pk_bf16_f32 v163, v68, v69
	ds_bpermute_b32 v192, v217, v160
	ds_bpermute_b32 v193, v217, v161
	ds_bpermute_b32 v194, v217, v162
	ds_bpermute_b32 v195, v217, v163
	s_waitcnt lgkmcnt(0)
	global_store_dwordx4 v216, v[180:183], s[10:11] sc0 sc1
	global_store_dwordx4 v216, v[184:187], s[10:11] offset:256 sc0 sc1
	global_store_dwordx4 v216, v[188:191], s[20:21] sc0 sc1
	global_store_dwordx4 v216, v[192:195], s[20:21] offset:256 sc0 sc1
	s_add_u32 s10, s22, 0x80000
	s_addc_u32 s11, s23, 0
	v_pk_mul_f32 v[62:63], v[62:63], s[6:7] op_sel_hi:[1,0]
	v_pk_mul_f32 v[64:65], v[64:65], s[6:7] op_sel_hi:[1,0]
	v_pk_mul_f32 v[58:59], v[58:59], s[6:7] op_sel_hi:[1,0]
	v_pk_mul_f32 v[60:61], v[60:61], s[6:7] op_sel_hi:[1,0]
	v_cvt_pk_bf16_f32 v148, v62, v63
	v_cvt_pk_bf16_f32 v149, v64, v65
	v_cvt_pk_bf16_f32 v150, v58, v59
	v_cvt_pk_bf16_f32 v151, v60, v61
	ds_bpermute_b32 v180, v217, v148
	ds_bpermute_b32 v181, v217, v149
	ds_bpermute_b32 v182, v217, v150
	ds_bpermute_b32 v183, v217, v151
	v_pk_mul_f32 v[54:55], v[54:55], s[6:7] op_sel_hi:[1,0]
	v_pk_mul_f32 v[56:57], v[56:57], s[6:7] op_sel_hi:[1,0]
	v_pk_mul_f32 v[50:51], v[50:51], s[6:7] op_sel_hi:[1,0]
	v_pk_mul_f32 v[52:53], v[52:53], s[6:7] op_sel_hi:[1,0]
	v_cvt_pk_bf16_f32 v152, v54, v55
	v_cvt_pk_bf16_f32 v153, v56, v57
	v_cvt_pk_bf16_f32 v154, v50, v51
	v_cvt_pk_bf16_f32 v155, v52, v53
	ds_bpermute_b32 v184, v217, v152
	ds_bpermute_b32 v185, v217, v153
	ds_bpermute_b32 v186, v217, v154
	ds_bpermute_b32 v187, v217, v155
	s_add_u32 s20, s22, 0x90000
	s_addc_u32 s21, s23, 0
	v_pk_mul_f32 v[46:47], v[46:47], s[6:7] op_sel_hi:[1,0]
	v_pk_mul_f32 v[48:49], v[48:49], s[6:7] op_sel_hi:[1,0]
	v_pk_mul_f32 v[42:43], v[42:43], s[6:7] op_sel_hi:[1,0]
	v_pk_mul_f32 v[44:45], v[44:45], s[6:7] op_sel_hi:[1,0]
	v_cvt_pk_bf16_f32 v156, v46, v47
	v_cvt_pk_bf16_f32 v157, v48, v49
	v_cvt_pk_bf16_f32 v158, v42, v43
	v_cvt_pk_bf16_f32 v159, v44, v45
	ds_bpermute_b32 v188, v217, v156
	ds_bpermute_b32 v189, v217, v157
	ds_bpermute_b32 v190, v217, v158
	ds_bpermute_b32 v191, v217, v159
	v_pk_mul_f32 v[38:39], v[38:39], s[6:7] op_sel_hi:[1,0]
	v_pk_mul_f32 v[40:41], v[40:41], s[6:7] op_sel_hi:[1,0]
	v_pk_mul_f32 v[34:35], v[34:35], s[6:7] op_sel_hi:[1,0]
	v_pk_mul_f32 v[36:37], v[36:37], s[6:7] op_sel_hi:[1,0]
	v_cvt_pk_bf16_f32 v160, v38, v39
	v_cvt_pk_bf16_f32 v161, v40, v41
	v_cvt_pk_bf16_f32 v162, v34, v35
	v_cvt_pk_bf16_f32 v163, v36, v37
	ds_bpermute_b32 v192, v217, v160
	ds_bpermute_b32 v193, v217, v161
	ds_bpermute_b32 v194, v217, v162
	ds_bpermute_b32 v195, v217, v163
	s_waitcnt lgkmcnt(0)
	global_store_dwordx4 v216, v[180:183], s[10:11] sc0 sc1
	global_store_dwordx4 v216, v[184:187], s[10:11] offset:256 sc0 sc1
	global_store_dwordx4 v216, v[188:191], s[20:21] sc0 sc1
	global_store_dwordx4 v216, v[192:195], s[20:21] offset:256 sc0 sc1
	s_add_u32 s10, s22, 0xa0000
	s_addc_u32 s11, s23, 0
	v_pk_mul_f32 v[28:29], v[28:29], s[6:7] op_sel_hi:[1,0]
	v_pk_mul_f32 v[30:31], v[30:31], s[6:7] op_sel_hi:[1,0]
	v_pk_mul_f32 v[24:25], v[24:25], s[6:7] op_sel_hi:[1,0]
	v_pk_mul_f32 v[26:27], v[26:27], s[6:7] op_sel_hi:[1,0]
	v_cvt_pk_bf16_f32 v148, v28, v29
	v_cvt_pk_bf16_f32 v149, v30, v31
	v_cvt_pk_bf16_f32 v150, v24, v25
	v_cvt_pk_bf16_f32 v151, v26, v27
	ds_bpermute_b32 v180, v217, v148
	ds_bpermute_b32 v181, v217, v149
	ds_bpermute_b32 v182, v217, v150
	ds_bpermute_b32 v183, v217, v151
	v_pk_mul_f32 v[20:21], v[20:21], s[6:7] op_sel_hi:[1,0]
	v_pk_mul_f32 v[22:23], v[22:23], s[6:7] op_sel_hi:[1,0]
	v_pk_mul_f32 v[16:17], v[16:17], s[6:7] op_sel_hi:[1,0]
	v_pk_mul_f32 v[18:19], v[18:19], s[6:7] op_sel_hi:[1,0]
	v_cvt_pk_bf16_f32 v152, v20, v21
	v_cvt_pk_bf16_f32 v153, v22, v23
	v_cvt_pk_bf16_f32 v154, v16, v17
	v_cvt_pk_bf16_f32 v155, v18, v19
	ds_bpermute_b32 v184, v217, v152
	ds_bpermute_b32 v185, v217, v153
	ds_bpermute_b32 v186, v217, v154
	ds_bpermute_b32 v187, v217, v155
	s_add_u32 s20, s22, 0xb0000
	s_addc_u32 s21, s23, 0
	v_pk_mul_f32 v[12:13], v[12:13], s[6:7] op_sel_hi:[1,0]
	v_pk_mul_f32 v[14:15], v[14:15], s[6:7] op_sel_hi:[1,0]
	v_pk_mul_f32 v[8:9], v[8:9], s[6:7] op_sel_hi:[1,0]
	v_pk_mul_f32 v[10:11], v[10:11], s[6:7] op_sel_hi:[1,0]
	v_cvt_pk_bf16_f32 v156, v12, v13
	v_cvt_pk_bf16_f32 v157, v14, v15
	v_cvt_pk_bf16_f32 v158, v8, v9
	v_cvt_pk_bf16_f32 v159, v10, v11
	ds_bpermute_b32 v188, v217, v156
	ds_bpermute_b32 v189, v217, v157
	ds_bpermute_b32 v190, v217, v158
	ds_bpermute_b32 v191, v217, v159
	v_pk_mul_f32 v[4:5], v[4:5], s[6:7] op_sel_hi:[1,0]
	v_pk_mul_f32 v[6:7], v[6:7], s[6:7] op_sel_hi:[1,0]
	v_pk_mul_f32 v[0:1], v[0:1], s[6:7] op_sel_hi:[1,0]
	v_pk_mul_f32 v[2:3], v[2:3], s[6:7] op_sel_hi:[1,0]
	v_cvt_pk_bf16_f32 v160, v4, v5
	v_cvt_pk_bf16_f32 v161, v6, v7
	v_cvt_pk_bf16_f32 v162, v0, v1
	v_cvt_pk_bf16_f32 v163, v2, v3
	ds_bpermute_b32 v192, v217, v160
	ds_bpermute_b32 v193, v217, v161
	ds_bpermute_b32 v194, v217, v162
	ds_bpermute_b32 v195, v217, v163
	s_waitcnt lgkmcnt(0)
	global_store_dwordx4 v216, v[180:183], s[10:11] sc0 sc1
	global_store_dwordx4 v216, v[184:187], s[10:11] offset:256 sc0 sc1
	global_store_dwordx4 v216, v[188:191], s[20:21] sc0 sc1
	global_store_dwordx4 v216, v[192:195], s[20:21] offset:256 sc0 sc1
	s_branch .LBB0_364
.Lmain_sig:
	s_mul_i32 s7, s31, 0x300000
	s_sub_i32 s6, s51, 0x44
	s_lshl_b32 s6, s6, 9
	s_add_i32 s7, s7, s6
	s_add_i32 s7, s7, 0x37f51000
	s_add_u32 s22, s76, s7
	s_addc_u32 s23, s77, 0
	v_mul_u32_u24_e32 v216, 0x3000, v216
	v_add_u32_e32 v216, v216, v210
	s_add_u32 s10, s22, 0
	s_addc_u32 s11, s23, 0
	v_mul_f32_e32 v208, 0xbfb8aa3b, v126
	v_mul_f32_e32 v209, 0xbfb8aa3b, v127
	v_mul_f32_e32 v210, 0xbfb8aa3b, v128
	v_mul_f32_e32 v211, 0xbfb8aa3b, v129
	v_mul_f32_e32 v212, 0xbfb8aa3b, v122
	v_mul_f32_e32 v213, 0xbfb8aa3b, v123
	v_mul_f32_e32 v214, 0xbfb8aa3b, v124
	v_mul_f32_e32 v215, 0xbfb8aa3b, v125
	v_exp_f32_e32 v208, v208
	v_exp_f32_e32 v209, v209
	v_exp_f32_e32 v210, v210
	v_exp_f32_e32 v211, v211
	v_exp_f32_e32 v212, v212
	v_exp_f32_e32 v213, v213
	v_exp_f32_e32 v214, v214
	v_exp_f32_e32 v215, v215
	v_add_f32_e32 v208, 1.0, v208
	v_add_f32_e32 v209, 1.0, v209
	v_add_f32_e32 v210, 1.0, v210
	v_add_f32_e32 v211, 1.0, v211
	v_add_f32_e32 v212, 1.0, v212
	v_add_f32_e32 v213, 1.0, v213
	v_add_f32_e32 v214, 1.0, v214
	v_add_f32_e32 v215, 1.0, v215
	v_rcp_f32_e32 v208, v208
	v_rcp_f32_e32 v209, v209
	v_rcp_f32_e32 v210, v210
	v_rcp_f32_e32 v211, v211
	v_rcp_f32_e32 v212, v212
	v_rcp_f32_e32 v213, v213
	v_rcp_f32_e32 v214, v214
	v_rcp_f32_e32 v215, v215
	v_cvt_pk_bf16_f32 v148, v208, v209
	v_cvt_pk_bf16_f32 v149, v210, v211
	v_cvt_pk_bf16_f32 v150, v212, v213
	v_cvt_pk_bf16_f32 v151, v214, v215
	ds_bpermute_b32 v180, v217, v148
	ds_bpermute_b32 v181, v217, v149
	ds_bpermute_b32 v182, v217, v150
	ds_bpermute_b32 v183, v217, v151
	v_mul_f32_e32 v208, 0xbfb8aa3b, v118
	v_mul_f32_e32 v209, 0xbfb8aa3b, v119
	v_mul_f32_e32 v210, 0xbfb8aa3b, v120
	v_mul_f32_e32 v211, 0xbfb8aa3b, v121
	v_mul_f32_e32 v212, 0xbfb8aa3b, v114
	v_mul_f32_e32 v213, 0xbfb8aa3b, v115
	v_mul_f32_e32 v214, 0xbfb8aa3b, v116
	v_mul_f32_e32 v215, 0xbfb8aa3b, v117
	v_exp_f32_e32 v208, v208
	v_exp_f32_e32 v209, v209
	v_exp_f32_e32 v210, v210
	v_exp_f32_e32 v211, v211
	v_exp_f32_e32 v212, v212
	v_exp_f32_e32 v213, v213
	v_exp_f32_e32 v214, v214
	v_exp_f32_e32 v215, v215
	v_add_f32_e32 v208, 1.0, v208
	v_add_f32_e32 v209, 1.0, v209
	v_add_f32_e32 v210, 1.0, v210
	v_add_f32_e32 v211, 1.0, v211
	v_add_f32_e32 v212, 1.0, v212
	v_add_f32_e32 v213, 1.0, v213
	v_add_f32_e32 v214, 1.0, v214
	v_add_f32_e32 v215, 1.0, v215
	v_rcp_f32_e32 v208, v208
	v_rcp_f32_e32 v209, v209
	v_rcp_f32_e32 v210, v210
	v_rcp_f32_e32 v211, v211
	v_rcp_f32_e32 v212, v212
	v_rcp_f32_e32 v213, v213
	v_rcp_f32_e32 v214, v214
	v_rcp_f32_e32 v215, v215
	v_cvt_pk_bf16_f32 v152, v208, v209
	v_cvt_pk_bf16_f32 v153, v210, v211
	v_cvt_pk_bf16_f32 v154, v212, v213
	v_cvt_pk_bf16_f32 v155, v214, v215
	ds_bpermute_b32 v184, v217, v152
	ds_bpermute_b32 v185, v217, v153
	ds_bpermute_b32 v186, v217, v154
	ds_bpermute_b32 v187, v217, v155
	s_add_u32 s20, s22, 0x30000
	s_addc_u32 s21, s23, 0
	v_mul_f32_e32 v208, 0xbfb8aa3b, v110
	v_mul_f32_e32 v209, 0xbfb8aa3b, v111
	v_mul_f32_e32 v210, 0xbfb8aa3b, v112
	v_mul_f32_e32 v211, 0xbfb8aa3b, v113
	v_mul_f32_e32 v212, 0xbfb8aa3b, v106
	v_mul_f32_e32 v213, 0xbfb8aa3b, v107
	v_mul_f32_e32 v214, 0xbfb8aa3b, v108
	v_mul_f32_e32 v215, 0xbfb8aa3b, v109
	v_exp_f32_e32 v208, v208
	v_exp_f32_e32 v209, v209
	v_exp_f32_e32 v210, v210
	v_exp_f32_e32 v211, v211
	v_exp_f32_e32 v212, v212
	v_exp_f32_e32 v213, v213
	v_exp_f32_e32 v214, v214
	v_exp_f32_e32 v215, v215
	v_add_f32_e32 v208, 1.0, v208
	v_add_f32_e32 v209, 1.0, v209
	v_add_f32_e32 v210, 1.0, v210
	v_add_f32_e32 v211, 1.0, v211
	v_add_f32_e32 v212, 1.0, v212
	v_add_f32_e32 v213, 1.0, v213
	v_add_f32_e32 v214, 1.0, v214
	v_add_f32_e32 v215, 1.0, v215
	v_rcp_f32_e32 v208, v208
	v_rcp_f32_e32 v209, v209
	v_rcp_f32_e32 v210, v210
	v_rcp_f32_e32 v211, v211
	v_rcp_f32_e32 v212, v212
	v_rcp_f32_e32 v213, v213
	v_rcp_f32_e32 v214, v214
	v_rcp_f32_e32 v215, v215
	v_cvt_pk_bf16_f32 v156, v208, v209
	v_cvt_pk_bf16_f32 v157, v210, v211
	v_cvt_pk_bf16_f32 v158, v212, v213
	v_cvt_pk_bf16_f32 v159, v214, v215
	ds_bpermute_b32 v188, v217, v156
	ds_bpermute_b32 v189, v217, v157
	ds_bpermute_b32 v190, v217, v158
	ds_bpermute_b32 v191, v217, v159
	v_mul_f32_e32 v208, 0xbfb8aa3b, v102
	v_mul_f32_e32 v209, 0xbfb8aa3b, v103
	v_mul_f32_e32 v210, 0xbfb8aa3b, v104
	v_mul_f32_e32 v211, 0xbfb8aa3b, v105
	v_mul_f32_e32 v212, 0xbfb8aa3b, v98
	v_mul_f32_e32 v213, 0xbfb8aa3b, v99
	v_mul_f32_e32 v214, 0xbfb8aa3b, v100
	v_mul_f32_e32 v215, 0xbfb8aa3b, v101
	v_exp_f32_e32 v208, v208
	v_exp_f32_e32 v209, v209
	v_exp_f32_e32 v210, v210
	v_exp_f32_e32 v211, v211
	v_exp_f32_e32 v212, v212
	v_exp_f32_e32 v213, v213
	v_exp_f32_e32 v214, v214
	v_exp_f32_e32 v215, v215
	v_add_f32_e32 v208, 1.0, v208
	v_add_f32_e32 v209, 1.0, v209
	v_add_f32_e32 v210, 1.0, v210
	v_add_f32_e32 v211, 1.0, v211
	v_add_f32_e32 v212, 1.0, v212
	v_add_f32_e32 v213, 1.0, v213
	v_add_f32_e32 v214, 1.0, v214
	v_add_f32_e32 v215, 1.0, v215
	v_rcp_f32_e32 v208, v208
	v_rcp_f32_e32 v209, v209
	v_rcp_f32_e32 v210, v210
	v_rcp_f32_e32 v211, v211
	v_rcp_f32_e32 v212, v212
	v_rcp_f32_e32 v213, v213
	v_rcp_f32_e32 v214, v214
	v_rcp_f32_e32 v215, v215
	v_cvt_pk_bf16_f32 v160, v208, v209
	v_cvt_pk_bf16_f32 v161, v210, v211
	v_cvt_pk_bf16_f32 v162, v212, v213
	v_cvt_pk_bf16_f32 v163, v214, v215
	ds_bpermute_b32 v192, v217, v160
	ds_bpermute_b32 v193, v217, v161
	ds_bpermute_b32 v194, v217, v162
	ds_bpermute_b32 v195, v217, v163
	s_waitcnt lgkmcnt(0)
	global_store_dwordx4 v216, v[180:183], s[10:11] sc0 sc1
	global_store_dwordx4 v216, v[184:187], s[10:11] offset:256 sc0 sc1
	global_store_dwordx4 v216, v[188:191], s[20:21] sc0 sc1
	global_store_dwordx4 v216, v[192:195], s[20:21] offset:256 sc0 sc1
	s_add_u32 s10, s22, 0x60000
	s_addc_u32 s11, s23, 0
	v_mul_f32_e32 v208, 0xbfb8aa3b, v94
	v_mul_f32_e32 v209, 0xbfb8aa3b, v95
	v_mul_f32_e32 v210, 0xbfb8aa3b, v96
	v_mul_f32_e32 v211, 0xbfb8aa3b, v97
	v_mul_f32_e32 v212, 0xbfb8aa3b, v90
	v_mul_f32_e32 v213, 0xbfb8aa3b, v91
	v_mul_f32_e32 v214, 0xbfb8aa3b, v92
	v_mul_f32_e32 v215, 0xbfb8aa3b, v93
	v_exp_f32_e32 v208, v208
	v_exp_f32_e32 v209, v209
	v_exp_f32_e32 v210, v210
	v_exp_f32_e32 v211, v211
	v_exp_f32_e32 v212, v212
	v_exp_f32_e32 v213, v213
	v_exp_f32_e32 v214, v214
	v_exp_f32_e32 v215, v215
	v_add_f32_e32 v208, 1.0, v208
	v_add_f32_e32 v209, 1.0, v209
	v_add_f32_e32 v210, 1.0, v210
	v_add_f32_e32 v211, 1.0, v211
	v_add_f32_e32 v212, 1.0, v212
	v_add_f32_e32 v213, 1.0, v213
	v_add_f32_e32 v214, 1.0, v214
	v_add_f32_e32 v215, 1.0, v215
	v_rcp_f32_e32 v208, v208
	v_rcp_f32_e32 v209, v209
	v_rcp_f32_e32 v210, v210
	v_rcp_f32_e32 v211, v211
	v_rcp_f32_e32 v212, v212
	v_rcp_f32_e32 v213, v213
	v_rcp_f32_e32 v214, v214
	v_rcp_f32_e32 v215, v215
	v_cvt_pk_bf16_f32 v148, v208, v209
	v_cvt_pk_bf16_f32 v149, v210, v211
	v_cvt_pk_bf16_f32 v150, v212, v213
	v_cvt_pk_bf16_f32 v151, v214, v215
	ds_bpermute_b32 v180, v217, v148
	ds_bpermute_b32 v181, v217, v149
	ds_bpermute_b32 v182, v217, v150
	ds_bpermute_b32 v183, v217, v151
	v_mul_f32_e32 v208, 0xbfb8aa3b, v86
	v_mul_f32_e32 v209, 0xbfb8aa3b, v87
	v_mul_f32_e32 v210, 0xbfb8aa3b, v88
	v_mul_f32_e32 v211, 0xbfb8aa3b, v89
	v_mul_f32_e32 v212, 0xbfb8aa3b, v82
	v_mul_f32_e32 v213, 0xbfb8aa3b, v83
	v_mul_f32_e32 v214, 0xbfb8aa3b, v84
	v_mul_f32_e32 v215, 0xbfb8aa3b, v85
	v_exp_f32_e32 v208, v208
	v_exp_f32_e32 v209, v209
	v_exp_f32_e32 v210, v210
	v_exp_f32_e32 v211, v211
	v_exp_f32_e32 v212, v212
	v_exp_f32_e32 v213, v213
	v_exp_f32_e32 v214, v214
	v_exp_f32_e32 v215, v215
	v_add_f32_e32 v208, 1.0, v208
	v_add_f32_e32 v209, 1.0, v209
	v_add_f32_e32 v210, 1.0, v210
	v_add_f32_e32 v211, 1.0, v211
	v_add_f32_e32 v212, 1.0, v212
	v_add_f32_e32 v213, 1.0, v213
	v_add_f32_e32 v214, 1.0, v214
	v_add_f32_e32 v215, 1.0, v215
	v_rcp_f32_e32 v208, v208
	v_rcp_f32_e32 v209, v209
	v_rcp_f32_e32 v210, v210
	v_rcp_f32_e32 v211, v211
	v_rcp_f32_e32 v212, v212
	v_rcp_f32_e32 v213, v213
	v_rcp_f32_e32 v214, v214
	v_rcp_f32_e32 v215, v215
	v_cvt_pk_bf16_f32 v152, v208, v209
	v_cvt_pk_bf16_f32 v153, v210, v211
	v_cvt_pk_bf16_f32 v154, v212, v213
	v_cvt_pk_bf16_f32 v155, v214, v215
	ds_bpermute_b32 v184, v217, v152
	ds_bpermute_b32 v185, v217, v153
	ds_bpermute_b32 v186, v217, v154
	ds_bpermute_b32 v187, v217, v155
	s_add_u32 s20, s22, 0x90000
	s_addc_u32 s21, s23, 0
	v_mul_f32_e32 v208, 0xbfb8aa3b, v78
	v_mul_f32_e32 v209, 0xbfb8aa3b, v79
	v_mul_f32_e32 v210, 0xbfb8aa3b, v80
	v_mul_f32_e32 v211, 0xbfb8aa3b, v81
	v_mul_f32_e32 v212, 0xbfb8aa3b, v74
	v_mul_f32_e32 v213, 0xbfb8aa3b, v75
	v_mul_f32_e32 v214, 0xbfb8aa3b, v76
	v_mul_f32_e32 v215, 0xbfb8aa3b, v77
	v_exp_f32_e32 v208, v208
	v_exp_f32_e32 v209, v209
	v_exp_f32_e32 v210, v210
	v_exp_f32_e32 v211, v211
	v_exp_f32_e32 v212, v212
	v_exp_f32_e32 v213, v213
	v_exp_f32_e32 v214, v214
	v_exp_f32_e32 v215, v215
	v_add_f32_e32 v208, 1.0, v208
	v_add_f32_e32 v209, 1.0, v209
	v_add_f32_e32 v210, 1.0, v210
	v_add_f32_e32 v211, 1.0, v211
	v_add_f32_e32 v212, 1.0, v212
	v_add_f32_e32 v213, 1.0, v213
	v_add_f32_e32 v214, 1.0, v214
	v_add_f32_e32 v215, 1.0, v215
	v_rcp_f32_e32 v208, v208
	v_rcp_f32_e32 v209, v209
	v_rcp_f32_e32 v210, v210
	v_rcp_f32_e32 v211, v211
	v_rcp_f32_e32 v212, v212
	v_rcp_f32_e32 v213, v213
	v_rcp_f32_e32 v214, v214
	v_rcp_f32_e32 v215, v215
	v_cvt_pk_bf16_f32 v156, v208, v209
	v_cvt_pk_bf16_f32 v157, v210, v211
	v_cvt_pk_bf16_f32 v158, v212, v213
	v_cvt_pk_bf16_f32 v159, v214, v215
	ds_bpermute_b32 v188, v217, v156
	ds_bpermute_b32 v189, v217, v157
	ds_bpermute_b32 v190, v217, v158
	ds_bpermute_b32 v191, v217, v159
	v_mul_f32_e32 v208, 0xbfb8aa3b, v70
	v_mul_f32_e32 v209, 0xbfb8aa3b, v71
	v_mul_f32_e32 v210, 0xbfb8aa3b, v72
	v_mul_f32_e32 v211, 0xbfb8aa3b, v73
	v_mul_f32_e32 v212, 0xbfb8aa3b, v66
	v_mul_f32_e32 v213, 0xbfb8aa3b, v67
	v_mul_f32_e32 v214, 0xbfb8aa3b, v68
	v_mul_f32_e32 v215, 0xbfb8aa3b, v69
	v_exp_f32_e32 v208, v208
	v_exp_f32_e32 v209, v209
	v_exp_f32_e32 v210, v210
	v_exp_f32_e32 v211, v211
	v_exp_f32_e32 v212, v212
	v_exp_f32_e32 v213, v213
	v_exp_f32_e32 v214, v214
	v_exp_f32_e32 v215, v215
	v_add_f32_e32 v208, 1.0, v208
	v_add_f32_e32 v209, 1.0, v209
	v_add_f32_e32 v210, 1.0, v210
	v_add_f32_e32 v211, 1.0, v211
	v_add_f32_e32 v212, 1.0, v212
	v_add_f32_e32 v213, 1.0, v213
	v_add_f32_e32 v214, 1.0, v214
	v_add_f32_e32 v215, 1.0, v215
	v_rcp_f32_e32 v208, v208
	v_rcp_f32_e32 v209, v209
	v_rcp_f32_e32 v210, v210
	v_rcp_f32_e32 v211, v211
	v_rcp_f32_e32 v212, v212
	v_rcp_f32_e32 v213, v213
	v_rcp_f32_e32 v214, v214
	v_rcp_f32_e32 v215, v215
	v_cvt_pk_bf16_f32 v160, v208, v209
	v_cvt_pk_bf16_f32 v161, v210, v211
	v_cvt_pk_bf16_f32 v162, v212, v213
	v_cvt_pk_bf16_f32 v163, v214, v215
	ds_bpermute_b32 v192, v217, v160
	ds_bpermute_b32 v193, v217, v161
	ds_bpermute_b32 v194, v217, v162
	ds_bpermute_b32 v195, v217, v163
	s_waitcnt lgkmcnt(0)
	global_store_dwordx4 v216, v[180:183], s[10:11] sc0 sc1
	global_store_dwordx4 v216, v[184:187], s[10:11] offset:256 sc0 sc1
	global_store_dwordx4 v216, v[188:191], s[20:21] sc0 sc1
	global_store_dwordx4 v216, v[192:195], s[20:21] offset:256 sc0 sc1
	s_add_u32 s10, s22, 0x180000
	s_addc_u32 s11, s23, 0
	v_mul_f32_e32 v208, 0xbfb8aa3b, v62
	v_mul_f32_e32 v209, 0xbfb8aa3b, v63
	v_mul_f32_e32 v210, 0xbfb8aa3b, v64
	v_mul_f32_e32 v211, 0xbfb8aa3b, v65
	v_mul_f32_e32 v212, 0xbfb8aa3b, v58
	v_mul_f32_e32 v213, 0xbfb8aa3b, v59
	v_mul_f32_e32 v214, 0xbfb8aa3b, v60
	v_mul_f32_e32 v215, 0xbfb8aa3b, v61
	v_exp_f32_e32 v208, v208
	v_exp_f32_e32 v209, v209
	v_exp_f32_e32 v210, v210
	v_exp_f32_e32 v211, v211
	v_exp_f32_e32 v212, v212
	v_exp_f32_e32 v213, v213
	v_exp_f32_e32 v214, v214
	v_exp_f32_e32 v215, v215
	v_add_f32_e32 v208, 1.0, v208
	v_add_f32_e32 v209, 1.0, v209
	v_add_f32_e32 v210, 1.0, v210
	v_add_f32_e32 v211, 1.0, v211
	v_add_f32_e32 v212, 1.0, v212
	v_add_f32_e32 v213, 1.0, v213
	v_add_f32_e32 v214, 1.0, v214
	v_add_f32_e32 v215, 1.0, v215
	v_rcp_f32_e32 v208, v208
	v_rcp_f32_e32 v209, v209
	v_rcp_f32_e32 v210, v210
	v_rcp_f32_e32 v211, v211
	v_rcp_f32_e32 v212, v212
	v_rcp_f32_e32 v213, v213
	v_rcp_f32_e32 v214, v214
	v_rcp_f32_e32 v215, v215
	v_cvt_pk_bf16_f32 v148, v208, v209
	v_cvt_pk_bf16_f32 v149, v210, v211
	v_cvt_pk_bf16_f32 v150, v212, v213
	v_cvt_pk_bf16_f32 v151, v214, v215
	ds_bpermute_b32 v180, v217, v148
	ds_bpermute_b32 v181, v217, v149
	ds_bpermute_b32 v182, v217, v150
	ds_bpermute_b32 v183, v217, v151
	v_mul_f32_e32 v208, 0xbfb8aa3b, v54
	v_mul_f32_e32 v209, 0xbfb8aa3b, v55
	v_mul_f32_e32 v210, 0xbfb8aa3b, v56
	v_mul_f32_e32 v211, 0xbfb8aa3b, v57
	v_mul_f32_e32 v212, 0xbfb8aa3b, v50
	v_mul_f32_e32 v213, 0xbfb8aa3b, v51
	v_mul_f32_e32 v214, 0xbfb8aa3b, v52
	v_mul_f32_e32 v215, 0xbfb8aa3b, v53
	v_exp_f32_e32 v208, v208
	v_exp_f32_e32 v209, v209
	v_exp_f32_e32 v210, v210
	v_exp_f32_e32 v211, v211
	v_exp_f32_e32 v212, v212
	v_exp_f32_e32 v213, v213
	v_exp_f32_e32 v214, v214
	v_exp_f32_e32 v215, v215
	v_add_f32_e32 v208, 1.0, v208
	v_add_f32_e32 v209, 1.0, v209
	v_add_f32_e32 v210, 1.0, v210
	v_add_f32_e32 v211, 1.0, v211
	v_add_f32_e32 v212, 1.0, v212
	v_add_f32_e32 v213, 1.0, v213
	v_add_f32_e32 v214, 1.0, v214
	v_add_f32_e32 v215, 1.0, v215
	v_rcp_f32_e32 v208, v208
	v_rcp_f32_e32 v209, v209
	v_rcp_f32_e32 v210, v210
	v_rcp_f32_e32 v211, v211
	v_rcp_f32_e32 v212, v212
	v_rcp_f32_e32 v213, v213
	v_rcp_f32_e32 v214, v214
	v_rcp_f32_e32 v215, v215
	v_cvt_pk_bf16_f32 v152, v208, v209
	v_cvt_pk_bf16_f32 v153, v210, v211
	v_cvt_pk_bf16_f32 v154, v212, v213
	v_cvt_pk_bf16_f32 v155, v214, v215
	ds_bpermute_b32 v184, v217, v152
	ds_bpermute_b32 v185, v217, v153
	ds_bpermute_b32 v186, v217, v154
	ds_bpermute_b32 v187, v217, v155
	s_add_u32 s20, s22, 0x1b0000
	s_addc_u32 s21, s23, 0
	v_mul_f32_e32 v208, 0xbfb8aa3b, v46
	v_mul_f32_e32 v209, 0xbfb8aa3b, v47
	v_mul_f32_e32 v210, 0xbfb8aa3b, v48
	v_mul_f32_e32 v211, 0xbfb8aa3b, v49
	v_mul_f32_e32 v212, 0xbfb8aa3b, v42
	v_mul_f32_e32 v213, 0xbfb8aa3b, v43
	v_mul_f32_e32 v214, 0xbfb8aa3b, v44
	v_mul_f32_e32 v215, 0xbfb8aa3b, v45
	v_exp_f32_e32 v208, v208
	v_exp_f32_e32 v209, v209
	v_exp_f32_e32 v210, v210
	v_exp_f32_e32 v211, v211
	v_exp_f32_e32 v212, v212
	v_exp_f32_e32 v213, v213
	v_exp_f32_e32 v214, v214
	v_exp_f32_e32 v215, v215
	v_add_f32_e32 v208, 1.0, v208
	v_add_f32_e32 v209, 1.0, v209
	v_add_f32_e32 v210, 1.0, v210
	v_add_f32_e32 v211, 1.0, v211
	v_add_f32_e32 v212, 1.0, v212
	v_add_f32_e32 v213, 1.0, v213
	v_add_f32_e32 v214, 1.0, v214
	v_add_f32_e32 v215, 1.0, v215
	v_rcp_f32_e32 v208, v208
	v_rcp_f32_e32 v209, v209
	v_rcp_f32_e32 v210, v210
	v_rcp_f32_e32 v211, v211
	v_rcp_f32_e32 v212, v212
	v_rcp_f32_e32 v213, v213
	v_rcp_f32_e32 v214, v214
	v_rcp_f32_e32 v215, v215
	v_cvt_pk_bf16_f32 v156, v208, v209
	v_cvt_pk_bf16_f32 v157, v210, v211
	v_cvt_pk_bf16_f32 v158, v212, v213
	v_cvt_pk_bf16_f32 v159, v214, v215
	ds_bpermute_b32 v188, v217, v156
	ds_bpermute_b32 v189, v217, v157
	ds_bpermute_b32 v190, v217, v158
	ds_bpermute_b32 v191, v217, v159
	v_mul_f32_e32 v208, 0xbfb8aa3b, v38
	v_mul_f32_e32 v209, 0xbfb8aa3b, v39
	v_mul_f32_e32 v210, 0xbfb8aa3b, v40
	v_mul_f32_e32 v211, 0xbfb8aa3b, v41
	v_mul_f32_e32 v212, 0xbfb8aa3b, v34
	v_mul_f32_e32 v213, 0xbfb8aa3b, v35
	v_mul_f32_e32 v214, 0xbfb8aa3b, v36
	v_mul_f32_e32 v215, 0xbfb8aa3b, v37
	v_exp_f32_e32 v208, v208
	v_exp_f32_e32 v209, v209
	v_exp_f32_e32 v210, v210
	v_exp_f32_e32 v211, v211
	v_exp_f32_e32 v212, v212
	v_exp_f32_e32 v213, v213
	v_exp_f32_e32 v214, v214
	v_exp_f32_e32 v215, v215
	v_add_f32_e32 v208, 1.0, v208
	v_add_f32_e32 v209, 1.0, v209
	v_add_f32_e32 v210, 1.0, v210
	v_add_f32_e32 v211, 1.0, v211
	v_add_f32_e32 v212, 1.0, v212
	v_add_f32_e32 v213, 1.0, v213
	v_add_f32_e32 v214, 1.0, v214
	v_add_f32_e32 v215, 1.0, v215
	v_rcp_f32_e32 v208, v208
	v_rcp_f32_e32 v209, v209
	v_rcp_f32_e32 v210, v210
	v_rcp_f32_e32 v211, v211
	v_rcp_f32_e32 v212, v212
	v_rcp_f32_e32 v213, v213
	v_rcp_f32_e32 v214, v214
	v_rcp_f32_e32 v215, v215
	v_cvt_pk_bf16_f32 v160, v208, v209
	v_cvt_pk_bf16_f32 v161, v210, v211
	v_cvt_pk_bf16_f32 v162, v212, v213
	v_cvt_pk_bf16_f32 v163, v214, v215
	ds_bpermute_b32 v192, v217, v160
	ds_bpermute_b32 v193, v217, v161
	ds_bpermute_b32 v194, v217, v162
	ds_bpermute_b32 v195, v217, v163
	s_waitcnt lgkmcnt(0)
	global_store_dwordx4 v216, v[180:183], s[10:11] sc0 sc1
	global_store_dwordx4 v216, v[184:187], s[10:11] offset:256 sc0 sc1
	global_store_dwordx4 v216, v[188:191], s[20:21] sc0 sc1
	global_store_dwordx4 v216, v[192:195], s[20:21] offset:256 sc0 sc1
	s_add_u32 s10, s22, 0x1e0000
	s_addc_u32 s11, s23, 0
	v_mul_f32_e32 v208, 0xbfb8aa3b, v28
	v_mul_f32_e32 v209, 0xbfb8aa3b, v29
	v_mul_f32_e32 v210, 0xbfb8aa3b, v30
	v_mul_f32_e32 v211, 0xbfb8aa3b, v31
	v_mul_f32_e32 v212, 0xbfb8aa3b, v24
	v_mul_f32_e32 v213, 0xbfb8aa3b, v25
	v_mul_f32_e32 v214, 0xbfb8aa3b, v26
	v_mul_f32_e32 v215, 0xbfb8aa3b, v27
	v_exp_f32_e32 v208, v208
	v_exp_f32_e32 v209, v209
	v_exp_f32_e32 v210, v210
	v_exp_f32_e32 v211, v211
	v_exp_f32_e32 v212, v212
	v_exp_f32_e32 v213, v213
	v_exp_f32_e32 v214, v214
	v_exp_f32_e32 v215, v215
	v_add_f32_e32 v208, 1.0, v208
	v_add_f32_e32 v209, 1.0, v209
	v_add_f32_e32 v210, 1.0, v210
	v_add_f32_e32 v211, 1.0, v211
	v_add_f32_e32 v212, 1.0, v212
	v_add_f32_e32 v213, 1.0, v213
	v_add_f32_e32 v214, 1.0, v214
	v_add_f32_e32 v215, 1.0, v215
	v_rcp_f32_e32 v208, v208
	v_rcp_f32_e32 v209, v209
	v_rcp_f32_e32 v210, v210
	v_rcp_f32_e32 v211, v211
	v_rcp_f32_e32 v212, v212
	v_rcp_f32_e32 v213, v213
	v_rcp_f32_e32 v214, v214
	v_rcp_f32_e32 v215, v215
	v_cvt_pk_bf16_f32 v148, v208, v209
	v_cvt_pk_bf16_f32 v149, v210, v211
	v_cvt_pk_bf16_f32 v150, v212, v213
	v_cvt_pk_bf16_f32 v151, v214, v215
	ds_bpermute_b32 v180, v217, v148
	ds_bpermute_b32 v181, v217, v149
	ds_bpermute_b32 v182, v217, v150
	ds_bpermute_b32 v183, v217, v151
	v_mul_f32_e32 v208, 0xbfb8aa3b, v20
	v_mul_f32_e32 v209, 0xbfb8aa3b, v21
	v_mul_f32_e32 v210, 0xbfb8aa3b, v22
	v_mul_f32_e32 v211, 0xbfb8aa3b, v23
	v_mul_f32_e32 v212, 0xbfb8aa3b, v16
	v_mul_f32_e32 v213, 0xbfb8aa3b, v17
	v_mul_f32_e32 v214, 0xbfb8aa3b, v18
	v_mul_f32_e32 v215, 0xbfb8aa3b, v19
	v_exp_f32_e32 v208, v208
	v_exp_f32_e32 v209, v209
	v_exp_f32_e32 v210, v210
	v_exp_f32_e32 v211, v211
	v_exp_f32_e32 v212, v212
	v_exp_f32_e32 v213, v213
	v_exp_f32_e32 v214, v214
	v_exp_f32_e32 v215, v215
	v_add_f32_e32 v208, 1.0, v208
	v_add_f32_e32 v209, 1.0, v209
	v_add_f32_e32 v210, 1.0, v210
	v_add_f32_e32 v211, 1.0, v211
	v_add_f32_e32 v212, 1.0, v212
	v_add_f32_e32 v213, 1.0, v213
	v_add_f32_e32 v214, 1.0, v214
	v_add_f32_e32 v215, 1.0, v215
	v_rcp_f32_e32 v208, v208
	v_rcp_f32_e32 v209, v209
	v_rcp_f32_e32 v210, v210
	v_rcp_f32_e32 v211, v211
	v_rcp_f32_e32 v212, v212
	v_rcp_f32_e32 v213, v213
	v_rcp_f32_e32 v214, v214
	v_rcp_f32_e32 v215, v215
	v_cvt_pk_bf16_f32 v152, v208, v209
	v_cvt_pk_bf16_f32 v153, v210, v211
	v_cvt_pk_bf16_f32 v154, v212, v213
	v_cvt_pk_bf16_f32 v155, v214, v215
	ds_bpermute_b32 v184, v217, v152
	ds_bpermute_b32 v185, v217, v153
	ds_bpermute_b32 v186, v217, v154
	ds_bpermute_b32 v187, v217, v155
	s_add_u32 s20, s22, 0x210000
	s_addc_u32 s21, s23, 0
	v_mul_f32_e32 v208, 0xbfb8aa3b, v12
	v_mul_f32_e32 v209, 0xbfb8aa3b, v13
	v_mul_f32_e32 v210, 0xbfb8aa3b, v14
	v_mul_f32_e32 v211, 0xbfb8aa3b, v15
	v_mul_f32_e32 v212, 0xbfb8aa3b, v8
	v_mul_f32_e32 v213, 0xbfb8aa3b, v9
	v_mul_f32_e32 v214, 0xbfb8aa3b, v10
	v_mul_f32_e32 v215, 0xbfb8aa3b, v11
	v_exp_f32_e32 v208, v208
	v_exp_f32_e32 v209, v209
	v_exp_f32_e32 v210, v210
	v_exp_f32_e32 v211, v211
	v_exp_f32_e32 v212, v212
	v_exp_f32_e32 v213, v213
	v_exp_f32_e32 v214, v214
	v_exp_f32_e32 v215, v215
	v_add_f32_e32 v208, 1.0, v208
	v_add_f32_e32 v209, 1.0, v209
	v_add_f32_e32 v210, 1.0, v210
	v_add_f32_e32 v211, 1.0, v211
	v_add_f32_e32 v212, 1.0, v212
	v_add_f32_e32 v213, 1.0, v213
	v_add_f32_e32 v214, 1.0, v214
	v_add_f32_e32 v215, 1.0, v215
	v_rcp_f32_e32 v208, v208
	v_rcp_f32_e32 v209, v209
	v_rcp_f32_e32 v210, v210
	v_rcp_f32_e32 v211, v211
	v_rcp_f32_e32 v212, v212
	v_rcp_f32_e32 v213, v213
	v_rcp_f32_e32 v214, v214
	v_rcp_f32_e32 v215, v215
	v_cvt_pk_bf16_f32 v156, v208, v209
	v_cvt_pk_bf16_f32 v157, v210, v211
	v_cvt_pk_bf16_f32 v158, v212, v213
	v_cvt_pk_bf16_f32 v159, v214, v215
	ds_bpermute_b32 v188, v217, v156
	ds_bpermute_b32 v189, v217, v157
	ds_bpermute_b32 v190, v217, v158
	ds_bpermute_b32 v191, v217, v159
	v_mul_f32_e32 v208, 0xbfb8aa3b, v4
	v_mul_f32_e32 v209, 0xbfb8aa3b, v5
	v_mul_f32_e32 v210, 0xbfb8aa3b, v6
	v_mul_f32_e32 v211, 0xbfb8aa3b, v7
	v_mul_f32_e32 v212, 0xbfb8aa3b, v0
	v_mul_f32_e32 v213, 0xbfb8aa3b, v1
	v_mul_f32_e32 v214, 0xbfb8aa3b, v2
	v_mul_f32_e32 v215, 0xbfb8aa3b, v3
	v_exp_f32_e32 v208, v208
	v_exp_f32_e32 v209, v209
	v_exp_f32_e32 v210, v210
	v_exp_f32_e32 v211, v211
	v_exp_f32_e32 v212, v212
	v_exp_f32_e32 v213, v213
	v_exp_f32_e32 v214, v214
	v_exp_f32_e32 v215, v215
	v_add_f32_e32 v208, 1.0, v208
	v_add_f32_e32 v209, 1.0, v209
	v_add_f32_e32 v210, 1.0, v210
	v_add_f32_e32 v211, 1.0, v211
	v_add_f32_e32 v212, 1.0, v212
	v_add_f32_e32 v213, 1.0, v213
	v_add_f32_e32 v214, 1.0, v214
	v_add_f32_e32 v215, 1.0, v215
	v_rcp_f32_e32 v208, v208
	v_rcp_f32_e32 v209, v209
	v_rcp_f32_e32 v210, v210
	v_rcp_f32_e32 v211, v211
	v_rcp_f32_e32 v212, v212
	v_rcp_f32_e32 v213, v213
	v_rcp_f32_e32 v214, v214
	v_rcp_f32_e32 v215, v215
	v_cvt_pk_bf16_f32 v160, v208, v209
	v_cvt_pk_bf16_f32 v161, v210, v211
	v_cvt_pk_bf16_f32 v162, v212, v213
	v_cvt_pk_bf16_f32 v163, v214, v215
	ds_bpermute_b32 v192, v217, v160
	ds_bpermute_b32 v193, v217, v161
	ds_bpermute_b32 v194, v217, v162
	ds_bpermute_b32 v195, v217, v163
	s_waitcnt lgkmcnt(0)
	global_store_dwordx4 v216, v[180:183], s[10:11] sc0 sc1
	global_store_dwordx4 v216, v[184:187], s[10:11] offset:256 sc0 sc1
	global_store_dwordx4 v216, v[188:191], s[20:21] sc0 sc1
	global_store_dwordx4 v216, v[192:195], s[20:21] offset:256 sc0 sc1
	s_branch .LBB0_364
